# v22 plus skipping the final grid barrier after the last ffn_dn (kernel end is the synchronisation point)
# speedup vs baseline: 1.0083x; 1.0033x over previous
; __device__ __forceinline__ unsigned xb_add(unsigned* p, unsigned v) { return __hip_atomic_fetch_add(p, v, __ATOMIC_RELAXED, __HIP_MEMORY_SCOPE_AGENT); }
; __device__ __forceinline__ void xcd_barrier(const XcdBarrier& b) {
;     asm volatile("s_waitcnt vmcnt(0)" ::: "memory");
;     __syncthreads();
;     if (threadIdx.x == 0) {
;         unsigned* bar = b.bar;
;         __builtin_amdgcn_s_waitcnt(0);
;         unsigned nloc = b.st[0], nx = b.st[1];
;         if (nloc == 0u) { xcd_barrier_complete(bar, b.x, nloc, nx); b.st[0] = nloc; b.st[1] = nx; }
;         const unsigned old = xb_add(&bar[XB_XSUB(b.x)], 1u);
.LBB0_1178:
	s_waitcnt vmcnt(0)
	v_readlane_b32 s98, v255, 16
	s_nop 3
	s_and_b32 s98, s98, s8
	s_cmp_lg_u32 s98, 0
	s_cbranch_scc1 .Lskip_final_gsync
	s_barrier
	s_mov_b64 s[0:1], exec
	v_readlane_b32 s2, v254, 58
	v_readlane_b32 s3, v254, 59
	s_and_b64 s[2:3], s[0:1], s[2:3]
	s_mov_b64 exec, s[2:3]
	s_cbranch_execnz .LBB0_1179
	s_getpc_b64 s[98:99]

; #define PH(k, call) do { if constexpr ((PHMASK >> (k)) & 1u) { call; } GSYNC(); } while (0)
; __global__ void __launch_bounds__(NTHREADS, 2) fwd_kernel(Params prm) {
;     ...
;             PH(11, ph_ffn_dn(prm, lds, l, ffn));
;         }
;     }
; }
.Lskip_final_gsync:
.LBB0_1220:
	s_endpgm
